# EP2: fast path for the fox-gate/NSA-gate column tile (cat4) + no store-drain waits at tile start (on T2)
# speedup vs baseline: 1.0733x; 1.0155x over previous
.LBB0_183:
	s_ashr_i32 s1, s0, 31
	s_lshl_b64 s[4:5], s[0:1], 18
	s_add_u32 s8, s48, s4
	s_addc_u32 s9, s49, s5
	s_ashr_i32 s45, s44, 31
	s_lshl_b64 s[6:7], s[44:45], 18
	v_mov_b32_e32 v38, v156
	s_add_u32 s10, s22, s6
	s_addc_u32 s11, s23, s7
	v_readfirstlane_b32 s12, v38
	s_ashr_i32 s1, s12, 6
	v_bfe_u32 v0, v38, 3, 3
	v_lshl_or_b32 v2, s1, 5, v0
	v_min_i32_e32 v4, 0x7f, v2
	v_or_b32_e32 v10, 8, v2
	v_or_b32_e32 v20, 16, v2
	v_or_b32_e32 v28, 24, v2
	v_ashrrev_i32_e32 v5, 31, v4
	v_lshrrev_b32_e32 v11, 1, v10
	v_min_i32_e32 v12, 0x7f, v10
	v_min_i32_e32 v22, 0x7f, v20
	v_min_i32_e32 v30, 0x7f, v28
	v_lshlrev_b64 v[4:5], 11, v[4:5]
	v_lshlrev_b32_e32 v0, 4, v38
	v_and_b32_e32 v40, 48, v38
	v_ashrrev_i32_e32 v3, 31, v2
	v_xor_b32_e32 v11, v11, v38
	v_ashrrev_i32_e32 v13, 31, v12
	v_ashrrev_i32_e32 v23, 31, v22
	v_ashrrev_i32_e32 v31, 31, v30
	v_lshl_add_u64 v[4:5], s[8:9], 0, v[4:5]
	v_and_b32_e32 v41, 0x70, v0
	v_bitop3_b32 v0, v0, v40, s19 bitop3:0x6c
	v_lshlrev_b64 v[6:7], 11, v[2:3]
	v_lshlrev_b64 v[12:13], 11, v[12:13]
	v_lshlrev_b32_e32 v11, 4, v11
	v_lshlrev_b64 v[22:23], 11, v[22:23]
	v_lshrrev_b32_e32 v29, 1, v28
	v_lshlrev_b64 v[30:31], 11, v[30:31]
	s_lshl_b32 s1, s1, 12
	v_lshl_add_u64 v[4:5], v[4:5], 0, v[0:1]
	v_lshl_add_u64 v[8:9], s[10:11], 0, v[6:7]
	v_lshl_add_u64 v[12:13], s[8:9], 0, v[12:13]
	v_and_b32_e32 v14, 0x70, v11
	v_ashrrev_i32_e32 v11, 31, v10
	v_lshl_add_u64 v[22:23], s[8:9], 0, v[22:23]
	v_xor_b32_e32 v29, v29, v38
	v_lshl_add_u64 v[30:31], s[8:9], 0, v[30:31]
	s_add_i32 s8, s1, 0x4000
	s_mov_b32 m0, s1
	v_lshl_add_u64 v[8:9], v[8:9], 0, v[0:1]
	v_mov_b32_e32 v15, v1
	v_lshlrev_b64 v[16:17], 11, v[10:11]
	v_lshlrev_b32_e32 v29, 4, v29
	s_barrier
	global_load_lds_dwordx4 v[4:5], off
	s_mov_b32 m0, s8
	v_lshl_add_u64 v[12:13], v[12:13], 0, v[14:15]
	v_lshl_add_u64 v[18:19], s[10:11], 0, v[16:17]
	v_ashrrev_i32_e32 v21, 31, v20
	v_and_b32_e32 v32, 0x70, v29
	v_ashrrev_i32_e32 v29, 31, v28
	global_load_lds_dwordx4 v[8:9], off
	s_or_b32 m0, s1, 0x400
	s_add_i32 s9, s1, 0x4400
	v_lshl_add_u64 v[18:19], v[18:19], 0, v[14:15]
	v_lshlrev_b64 v[24:25], 11, v[20:21]
	v_lshlrev_b64 v[34:35], 11, v[28:29]
	global_load_lds_dwordx4 v[12:13], off
	s_mov_b32 m0, s9
	v_lshl_add_u64 v[22:23], v[22:23], 0, v[0:1]
	v_lshl_add_u64 v[26:27], s[10:11], 0, v[24:25]
	v_lshl_add_u64 v[36:37], s[10:11], 0, v[34:35]
	global_load_lds_dwordx4 v[18:19], off
	s_or_b32 m0, s1, 0x800
	s_add_i32 s10, s1, 0x4800
	v_lshl_add_u64 v[26:27], v[26:27], 0, v[0:1]
	v_mov_b32_e32 v33, v1
	global_load_lds_dwordx4 v[22:23], off
	s_mov_b32 m0, s10
	v_lshl_add_u64 v[30:31], v[30:31], 0, v[32:33]
	global_load_lds_dwordx4 v[26:27], off
	s_or_b32 m0, s1, 0xc00
	s_add_i32 s11, s1, 0x4c00
	v_lshl_add_u64 v[36:37], v[36:37], 0, v[32:33]
	global_load_lds_dwordx4 v[30:31], off
	s_mov_b32 m0, s11
	s_lshr_b32 s13, s12, 1
	global_load_lds_dwordx4 v[36:37], off
	v_and_b32_e32 v39, 31, v38
	s_and_b32 s13, s13, 0x1ffffc0
	v_or_b32_e32 v9, s13, v39
	v_cmp_gt_i64_e32 vcc, s[30:31], v[2:3]
	s_mul_i32 s13, s2, 0x7c0000
	s_add_u32 s6, s13, s6
	v_cndmask_b32_e32 v3, 0, v3, vcc
	v_cndmask_b32_e32 v2, v164, v2, vcc
	s_mul_hi_u32 s13, s2, 0x7c0000
	v_lshlrev_b64 v[2:3], 11, v[2:3]
	s_addc_u32 s7, s13, s7
	v_lshl_add_u64 v[66:67], s[4:5], 0, v[2:3]
	v_lshl_add_u64 v[2:3], s[6:7], 0, v[6:7]
	v_cmp_gt_i64_e32 vcc, s[30:31], v[10:11]
	v_lshl_add_u64 v[68:69], v[2:3], 0, v[0:1]
	v_bfe_u32 v4, v38, 5, 1
	v_cndmask_b32_e32 v3, 0, v11, vcc
	v_cndmask_b32_e32 v2, v164, v10, vcc
	v_lshlrev_b64 v[2:3], 11, v[2:3]
	v_lshrrev_b32_e32 v5, 1, v38
	v_lshl_add_u64 v[70:71], s[4:5], 0, v[2:3]
	v_lshl_add_u64 v[2:3], s[6:7], 0, v[16:17]
	v_cmp_gt_i64_e32 vcc, s[30:31], v[20:21]
	v_and_or_b32 v12, s12, 64, v39
	v_bitop3_b32 v5, v4, v5, 7 bitop3:0x78
	v_lshl_add_u64 v[72:73], v[2:3], 0, v[14:15]
	v_cndmask_b32_e32 v3, 0, v21, vcc
	v_cndmask_b32_e32 v2, v164, v20, vcc
	v_bfe_u32 v8, v38, 1, 3
	v_lshlrev_b32_e32 v9, 7, v9
	v_lshl_or_b32 v12, v12, 7, v163
	v_lshlrev_b32_e32 v5, 4, v5
	v_lshlrev_b64 v[2:3], 11, v[2:3]
	v_or_b32_e32 v98, v9, v5
	v_or_b32_e32 v99, v12, v5
	v_bitop3_b32 v5, v4, v8, 2 bitop3:0x36
	v_lshl_add_u64 v[74:75], s[4:5], 0, v[2:3]
	v_lshl_add_u64 v[2:3], s[6:7], 0, v[24:25]
	v_cmp_gt_i64_e32 vcc, s[30:31], v[28:29]
	v_lshlrev_b32_e32 v5, 4, v5
	v_lshl_add_u64 v[76:77], v[2:3], 0, v[0:1]
	v_cndmask_b32_e32 v3, 0, v29, vcc
	v_cndmask_b32_e32 v2, v164, v28, vcc
	s_waitcnt vmcnt(0)
	v_or_b32_e32 v100, v9, v5
	v_or_b32_e32 v101, v12, v5
	v_bitop3_b32 v5, v4, v8, 4 bitop3:0x36
	v_bitop3_b32 v4, v4, v8, 6 bitop3:0x36
	v_lshlrev_b64 v[2:3], 11, v[2:3]
	v_lshlrev_b32_e32 v5, 4, v5
	v_lshlrev_b32_e32 v4, 4, v4
	v_lshl_add_u64 v[78:79], s[4:5], 0, v[2:3]
	v_lshl_add_u64 v[2:3], s[6:7], 0, v[34:35]
	v_mov_b32_e32 v34, 0
	v_or_b32_e32 v102, v9, v5
	v_or_b32_e32 v103, v12, v5
	v_or_b32_e32 v104, v9, v4
	v_or_b32_e32 v105, v12, v4
	s_mov_b32 s12, 0
	v_bitop3_b32 v66, v66, v41, v40 bitop3:0xf6
	v_or_b32_e32 v70, v70, v14
	v_bitop3_b32 v74, v74, v41, v40 bitop3:0xf6
	v_or_b32_e32 v78, v78, v32
	v_lshl_add_u64 v[80:81], v[2:3], 0, v[32:33]
	s_add_i32 s6, s1, 0x8000
	s_add_i32 s7, s1, 0xc000
	s_add_i32 s13, s1, 0x8400
	s_add_i32 s14, s1, 0xc400
	s_add_i32 s15, s1, 0x8800
	s_add_i32 s16, s1, 0xc800
	s_add_i32 s17, s1, 0x8c00
	s_add_i32 s25, s1, 0xcc00
	v_mov_b32_e32 v35, v34
	v_mov_b32_e32 v36, v34
	v_mov_b32_e32 v37, v34
	v_mov_b32_e32 v38, v34
	v_mov_b32_e32 v39, v34
	v_mov_b32_e32 v40, v34
	v_mov_b32_e32 v41, v34
	v_mov_b32_e32 v42, v34
	v_mov_b32_e32 v43, v34
	v_mov_b32_e32 v44, v34
	v_mov_b32_e32 v45, v34
	v_mov_b32_e32 v46, v34
	v_mov_b32_e32 v47, v34
	v_mov_b32_e32 v48, v34
	v_mov_b32_e32 v49, v34
	v_mov_b32_e32 v2, v34
	v_mov_b32_e32 v3, v34
	v_mov_b32_e32 v4, v34
	v_mov_b32_e32 v5, v34
	v_mov_b32_e32 v6, v34
	v_mov_b32_e32 v7, v34
	v_mov_b32_e32 v8, v34
	v_mov_b32_e32 v9, v34
	v_mov_b32_e32 v10, v34
	v_mov_b32_e32 v11, v34
	v_mov_b32_e32 v12, v34
	v_mov_b32_e32 v13, v34
	v_mov_b32_e32 v14, v34
	v_mov_b32_e32 v15, v34
	v_mov_b32_e32 v16, v34
	v_mov_b32_e32 v17, v34
	v_mov_b32_e32 v50, v34
	v_mov_b32_e32 v51, v34
	v_mov_b32_e32 v52, v34
	v_mov_b32_e32 v53, v34
	v_mov_b32_e32 v54, v34
	v_mov_b32_e32 v55, v34
	v_mov_b32_e32 v56, v34
	v_mov_b32_e32 v57, v34
	v_mov_b32_e32 v58, v34
	v_mov_b32_e32 v59, v34
	v_mov_b32_e32 v60, v34
	v_mov_b32_e32 v61, v34
	v_mov_b32_e32 v62, v34
	v_mov_b32_e32 v63, v34
	v_mov_b32_e32 v64, v34
	v_mov_b32_e32 v65, v34
	v_mov_b32_e32 v18, v34
	v_mov_b32_e32 v19, v34
	v_mov_b32_e32 v20, v34
	v_mov_b32_e32 v21, v34
	v_mov_b32_e32 v22, v34
	v_mov_b32_e32 v23, v34
	v_mov_b32_e32 v24, v34
	v_mov_b32_e32 v25, v34
	v_mov_b32_e32 v26, v34
	v_mov_b32_e32 v27, v34
	v_mov_b32_e32 v28, v34
	v_mov_b32_e32 v29, v34
	v_mov_b32_e32 v30, v34
	v_mov_b32_e32 v31, v34
	v_mov_b32_e32 v32, v34
	v_mov_b32_e32 v33, v34
	s_waitcnt vmcnt(0) lgkmcnt(0)
	s_barrier
	v_lshl_add_u64 v[66:67], s[80:81], 0, v[66:67]
	v_lshl_add_u64 v[66:67], v[66:67], 0, s[64:65]
	v_lshl_add_u64 v[68:69], s[80:81], 0, v[68:69]
	v_lshl_add_u64 v[68:69], v[68:69], 0, s[66:67]
	v_lshl_add_u64 v[70:71], s[80:81], 0, v[70:71]
	v_lshl_add_u64 v[70:71], v[70:71], 0, s[64:65]
	v_lshl_add_u64 v[72:73], s[80:81], 0, v[72:73]
	v_lshl_add_u64 v[72:73], v[72:73], 0, s[66:67]
	v_lshl_add_u64 v[74:75], s[80:81], 0, v[74:75]
	v_lshl_add_u64 v[74:75], v[74:75], 0, s[64:65]
	v_lshl_add_u64 v[76:77], s[80:81], 0, v[76:77]
	v_lshl_add_u64 v[76:77], v[76:77], 0, s[66:67]
	v_lshl_add_u64 v[78:79], s[80:81], 0, v[78:79]
	v_lshl_add_u64 v[78:79], v[78:79], 0, s[64:65]
	v_lshl_add_u64 v[80:81], s[80:81], 0, v[80:81]
	v_lshl_add_u64 v[80:81], v[80:81], 0, s[66:67]
	s_mov_b32 m0, s6
	s_nop 0
	global_load_lds_dwordx4 v[66:67], off
	v_lshl_add_u64 v[66:67], v[66:67], 0, s[34:35]
	s_mov_b32 m0, s7
	s_nop 0
	global_load_lds_dwordx4 v[68:69], off
	v_lshl_add_u64 v[68:69], v[68:69], 0, s[34:35]
	s_mov_b32 m0, s13
	s_nop 0
	global_load_lds_dwordx4 v[70:71], off
	v_lshl_add_u64 v[70:71], v[70:71], 0, s[34:35]
	s_mov_b32 m0, s14
	s_nop 0
	global_load_lds_dwordx4 v[72:73], off
	v_lshl_add_u64 v[72:73], v[72:73], 0, s[34:35]
	s_mov_b32 m0, s15
	s_nop 0
	global_load_lds_dwordx4 v[74:75], off
	v_lshl_add_u64 v[74:75], v[74:75], 0, s[34:35]
	s_mov_b32 m0, s16
	s_nop 0
	global_load_lds_dwordx4 v[76:77], off
	v_lshl_add_u64 v[76:77], v[76:77], 0, s[34:35]
	s_mov_b32 m0, s17
	s_nop 0
	global_load_lds_dwordx4 v[78:79], off
	v_lshl_add_u64 v[78:79], v[78:79], 0, s[34:35]
	s_mov_b32 m0, s25
	s_nop 0
	global_load_lds_dwordx4 v[80:81], off
	v_lshl_add_u64 v[80:81], v[80:81], 0, s[34:35]
	s_mov_b32 s12, 0

.LBB0_187:
	v_mov_b32_e32 v73, v156
	s_nop 15
	s_nop 7
	s_mov_b64 s[6:7], exec
	v_lshrrev_b32_e32 v77, 6, v156
	v_and_b32_e32 v66, 63, v156
	v_readfirstlane_b32 s4, v77
	s_and_b32 s5, s4, 1
	s_lshr_b32 s8, s4, 1
	s_lshl_b32 s9, s44, 1
	s_add_u32 s9, s9, s5
	s_cmp_eq_u32 s9, 60
	s_cbranch_scc1 .Lep_cat4
	s_cmp_gt_u32 s9, 60
	s_cbranch_scc1 .LBB0_173
	s_cmp_lt_u32 s9, 4
	s_cbranch_scc0 .Lep_g0_no
	s_movk_i32 s10, 122
	s_movk_i32 s11, 0
	s_movk_i32 s12, 2
	s_movk_i32 s13, 0
	s_mov_b32 s14, 0x3e38aa3b
	s_movk_i32 s15, 1
	s_branch .Lep_decoded

.Lep_cat4:
	s_and_b32 s26, s0, 63
	s_lshl_b32 s26, s26, 7
	s_lshl_b32 s27, s8, 6
	s_add_u32 s26, s26, s27
	s_lshr_b32 s17, s0, 6
	v_and_b32_e32 v67, 31, v66
	v_lshrrev_b32_e32 v68, 5, v66
	v_cmp_gt_u32_e32 vcc, 28, v67
	s_and_saveexec_b64 s[92:93], vcc
	s_cbranch_execz .Lep_cat4_done
	v_cmp_gt_u32_e64 s[84:85], 4, v67
	v_readlane_b32 s72, v234, 6
	v_readlane_b32 s73, v234, 7
	s_lshl_b32 s16, s2, 2
	v_and_b32_e32 v77, 3, v67
	v_add_u32_e32 v77, s16, v77
	v_lshlrev_b32_e32 v77, 2, v77
	global_load_dword v78, v77, s[72:73]
	v_lshl_add_u32 v79, v68, 2, s26
	s_lshl_b32 s16, s17, 2
	v_add_u32_e32 v80, s16, v67
	v_lshl_add_u32 v80, v80, 13, v79
	v_lshlrev_b32_e32 v80, 2, v80
	v_add_u32_e32 v80, 0xd200000, v80
	s_lshl_b32 s16, s17, 13
	v_add_u32_e32 v81, s16, v79
	v_mul_u32_u24_e32 v81, 24, v81
	v_add_u32_e32 v81, v81, v67
	v_lshlrev_b32_e32 v81, 2, v81
	v_add_u32_e32 v81, 0xd2ffff0, v81
	v_cndmask_b32_e64 v75, v81, v80, s[84:85]
	v_mov_b32_e32 v82, 0x60
	v_cndmask_b32_e64 v69, v82, 4, s[84:85]
	s_waitcnt vmcnt(0)
	v_cndmask_b32_e64 v72, 0, v78, s[84:85]
	v_add_f32_e32 v83, v18, v72
	v_and_b32_e32 v84, 0x7fffffff, v83
	v_cndmask_b32_e64 v85, v18, v84, s[84:85]
	v_mul_f32_e32 v85, 0xbfb8aa3b, v85
	v_exp_f32_e32 v86, v85
	v_min_f32_e32 v147, 0, v83
	v_add_f32_e32 v87, 1.0, v86
	v_mad_u32_u24 v148, v69, 0, v75
	v_rcp_f32_e32 v144, v87
	v_log_f32_e32 v145, v87
	v_add_f32_e32 v146, -1.0, v87
	v_sub_f32_e32 v146, v146, v86
	v_mul_f32_e32 v146, v146, v144
	v_fma_f32 v145, v145, v124, -v146
	v_sub_f32_e32 v147, v147, v145
	v_mul_f32_e32 v147, 0x3fb8aa3b, v147
	v_cndmask_b32_e64 v147, v144, v147, s[84:85]
	global_store_dword v148, v147, s[80:81]
	v_add_f32_e32 v149, v19, v72
	v_and_b32_e32 v150, 0x7fffffff, v149
	v_cndmask_b32_e64 v151, v19, v150, s[84:85]
	v_mul_f32_e32 v151, 0xbfb8aa3b, v151
	v_exp_f32_e32 v152, v151
	v_min_f32_e32 v181, 0, v149
	v_add_f32_e32 v153, 1.0, v152
	v_mad_u32_u24 v182, v69, 1, v75
	v_rcp_f32_e32 v154, v153
	v_log_f32_e32 v155, v153
	v_add_f32_e32 v180, -1.0, v153
	v_sub_f32_e32 v180, v180, v152
	v_mul_f32_e32 v180, v180, v154
	v_fma_f32 v155, v155, v124, -v180
	v_sub_f32_e32 v181, v181, v155
	v_mul_f32_e32 v181, 0x3fb8aa3b, v181
	v_cndmask_b32_e64 v181, v154, v181, s[84:85]
	global_store_dword v182, v181, s[80:81]
	v_add_f32_e32 v83, v20, v72
	v_and_b32_e32 v84, 0x7fffffff, v83
	v_cndmask_b32_e64 v85, v20, v84, s[84:85]
	v_mul_f32_e32 v85, 0xbfb8aa3b, v85
	v_exp_f32_e32 v86, v85
	v_min_f32_e32 v147, 0, v83
	v_add_f32_e32 v87, 1.0, v86
	v_mad_u32_u24 v148, v69, 2, v75
	v_rcp_f32_e32 v144, v87
	v_log_f32_e32 v145, v87
	v_add_f32_e32 v146, -1.0, v87
	v_sub_f32_e32 v146, v146, v86
	v_mul_f32_e32 v146, v146, v144
	v_fma_f32 v145, v145, v124, -v146
	v_sub_f32_e32 v147, v147, v145
	v_mul_f32_e32 v147, 0x3fb8aa3b, v147
	v_cndmask_b32_e64 v147, v144, v147, s[84:85]
	global_store_dword v148, v147, s[80:81]
	v_add_f32_e32 v149, v21, v72
	v_and_b32_e32 v150, 0x7fffffff, v149
	v_cndmask_b32_e64 v151, v21, v150, s[84:85]
	v_mul_f32_e32 v151, 0xbfb8aa3b, v151
	v_exp_f32_e32 v152, v151
	v_min_f32_e32 v181, 0, v149
	v_add_f32_e32 v153, 1.0, v152
	v_mad_u32_u24 v182, v69, 3, v75
	v_rcp_f32_e32 v154, v153
	v_log_f32_e32 v155, v153
	v_add_f32_e32 v180, -1.0, v153
	v_sub_f32_e32 v180, v180, v152
	v_mul_f32_e32 v180, v180, v154
	v_fma_f32 v155, v155, v124, -v180
	v_sub_f32_e32 v181, v181, v155
	v_mul_f32_e32 v181, 0x3fb8aa3b, v181
	v_cndmask_b32_e64 v181, v154, v181, s[84:85]
	global_store_dword v182, v181, s[80:81]
	v_add_f32_e32 v83, v22, v72
	v_and_b32_e32 v84, 0x7fffffff, v83
	v_cndmask_b32_e64 v85, v22, v84, s[84:85]
	v_mul_f32_e32 v85, 0xbfb8aa3b, v85
	v_exp_f32_e32 v86, v85
	v_min_f32_e32 v147, 0, v83
	v_add_f32_e32 v87, 1.0, v86
	v_mad_u32_u24 v148, v69, 8, v75
	v_rcp_f32_e32 v144, v87
	v_log_f32_e32 v145, v87
	v_add_f32_e32 v146, -1.0, v87
	v_sub_f32_e32 v146, v146, v86
	v_mul_f32_e32 v146, v146, v144
	v_fma_f32 v145, v145, v124, -v146
	v_sub_f32_e32 v147, v147, v145
	v_mul_f32_e32 v147, 0x3fb8aa3b, v147
	v_cndmask_b32_e64 v147, v144, v147, s[84:85]
	global_store_dword v148, v147, s[80:81]
	v_add_f32_e32 v149, v23, v72
	v_and_b32_e32 v150, 0x7fffffff, v149
	v_cndmask_b32_e64 v151, v23, v150, s[84:85]
	v_mul_f32_e32 v151, 0xbfb8aa3b, v151
	v_exp_f32_e32 v152, v151
	v_min_f32_e32 v181, 0, v149
	v_add_f32_e32 v153, 1.0, v152
	v_mad_u32_u24 v182, v69, 9, v75
	v_rcp_f32_e32 v154, v153
	v_log_f32_e32 v155, v153
	v_add_f32_e32 v180, -1.0, v153
	v_sub_f32_e32 v180, v180, v152
	v_mul_f32_e32 v180, v180, v154
	v_fma_f32 v155, v155, v124, -v180
	v_sub_f32_e32 v181, v181, v155
	v_mul_f32_e32 v181, 0x3fb8aa3b, v181
	v_cndmask_b32_e64 v181, v154, v181, s[84:85]
	global_store_dword v182, v181, s[80:81]
	v_add_f32_e32 v83, v24, v72
	v_and_b32_e32 v84, 0x7fffffff, v83
	v_cndmask_b32_e64 v85, v24, v84, s[84:85]
	v_mul_f32_e32 v85, 0xbfb8aa3b, v85
	v_exp_f32_e32 v86, v85
	v_min_f32_e32 v147, 0, v83
	v_add_f32_e32 v87, 1.0, v86
	v_mad_u32_u24 v148, v69, 10, v75
	v_rcp_f32_e32 v144, v87
	v_log_f32_e32 v145, v87
	v_add_f32_e32 v146, -1.0, v87
	v_sub_f32_e32 v146, v146, v86
	v_mul_f32_e32 v146, v146, v144
	v_fma_f32 v145, v145, v124, -v146
	v_sub_f32_e32 v147, v147, v145
	v_mul_f32_e32 v147, 0x3fb8aa3b, v147
	v_cndmask_b32_e64 v147, v144, v147, s[84:85]
	global_store_dword v148, v147, s[80:81]
	v_add_f32_e32 v149, v25, v72
	v_and_b32_e32 v150, 0x7fffffff, v149
	v_cndmask_b32_e64 v151, v25, v150, s[84:85]
	v_mul_f32_e32 v151, 0xbfb8aa3b, v151
	v_exp_f32_e32 v152, v151
	v_min_f32_e32 v181, 0, v149
	v_add_f32_e32 v153, 1.0, v152
	v_mad_u32_u24 v182, v69, 11, v75
	v_rcp_f32_e32 v154, v153
	v_log_f32_e32 v155, v153
	v_add_f32_e32 v180, -1.0, v153
	v_sub_f32_e32 v180, v180, v152
	v_mul_f32_e32 v180, v180, v154
	v_fma_f32 v155, v155, v124, -v180
	v_sub_f32_e32 v181, v181, v155
	v_mul_f32_e32 v181, 0x3fb8aa3b, v181
	v_cndmask_b32_e64 v181, v154, v181, s[84:85]
	global_store_dword v182, v181, s[80:81]
	v_add_f32_e32 v83, v26, v72
	v_and_b32_e32 v84, 0x7fffffff, v83
	v_cndmask_b32_e64 v85, v26, v84, s[84:85]
	v_mul_f32_e32 v85, 0xbfb8aa3b, v85
	v_exp_f32_e32 v86, v85
	v_min_f32_e32 v147, 0, v83
	v_add_f32_e32 v87, 1.0, v86
	v_mad_u32_u24 v148, v69, 16, v75
	v_rcp_f32_e32 v144, v87
	v_log_f32_e32 v145, v87
	v_add_f32_e32 v146, -1.0, v87
	v_sub_f32_e32 v146, v146, v86
	v_mul_f32_e32 v146, v146, v144
	v_fma_f32 v145, v145, v124, -v146
	v_sub_f32_e32 v147, v147, v145
	v_mul_f32_e32 v147, 0x3fb8aa3b, v147
	v_cndmask_b32_e64 v147, v144, v147, s[84:85]
	global_store_dword v148, v147, s[80:81]
	v_add_f32_e32 v149, v27, v72
	v_and_b32_e32 v150, 0x7fffffff, v149
	v_cndmask_b32_e64 v151, v27, v150, s[84:85]
	v_mul_f32_e32 v151, 0xbfb8aa3b, v151
	v_exp_f32_e32 v152, v151
	v_min_f32_e32 v181, 0, v149
	v_add_f32_e32 v153, 1.0, v152
	v_mad_u32_u24 v182, v69, 17, v75
	v_rcp_f32_e32 v154, v153
	v_log_f32_e32 v155, v153
	v_add_f32_e32 v180, -1.0, v153
	v_sub_f32_e32 v180, v180, v152
	v_mul_f32_e32 v180, v180, v154
	v_fma_f32 v155, v155, v124, -v180
	v_sub_f32_e32 v181, v181, v155
	v_mul_f32_e32 v181, 0x3fb8aa3b, v181
	v_cndmask_b32_e64 v181, v154, v181, s[84:85]
	global_store_dword v182, v181, s[80:81]
	v_add_f32_e32 v83, v28, v72
	v_and_b32_e32 v84, 0x7fffffff, v83
	v_cndmask_b32_e64 v85, v28, v84, s[84:85]
	v_mul_f32_e32 v85, 0xbfb8aa3b, v85
	v_exp_f32_e32 v86, v85
	v_min_f32_e32 v147, 0, v83
	v_add_f32_e32 v87, 1.0, v86
	v_mad_u32_u24 v148, v69, 18, v75
	v_rcp_f32_e32 v144, v87
	v_log_f32_e32 v145, v87
	v_add_f32_e32 v146, -1.0, v87
	v_sub_f32_e32 v146, v146, v86
	v_mul_f32_e32 v146, v146, v144
	v_fma_f32 v145, v145, v124, -v146
	v_sub_f32_e32 v147, v147, v145
	v_mul_f32_e32 v147, 0x3fb8aa3b, v147
	v_cndmask_b32_e64 v147, v144, v147, s[84:85]
	global_store_dword v148, v147, s[80:81]
	v_add_f32_e32 v149, v29, v72
	v_and_b32_e32 v150, 0x7fffffff, v149
	v_cndmask_b32_e64 v151, v29, v150, s[84:85]
	v_mul_f32_e32 v151, 0xbfb8aa3b, v151
	v_exp_f32_e32 v152, v151
	v_min_f32_e32 v181, 0, v149
	v_add_f32_e32 v153, 1.0, v152
	v_mad_u32_u24 v182, v69, 19, v75
	v_rcp_f32_e32 v154, v153
	v_log_f32_e32 v155, v153
	v_add_f32_e32 v180, -1.0, v153
	v_sub_f32_e32 v180, v180, v152
	v_mul_f32_e32 v180, v180, v154
	v_fma_f32 v155, v155, v124, -v180
	v_sub_f32_e32 v181, v181, v155
	v_mul_f32_e32 v181, 0x3fb8aa3b, v181
	v_cndmask_b32_e64 v181, v154, v181, s[84:85]
	global_store_dword v182, v181, s[80:81]
	v_add_f32_e32 v83, v30, v72
	v_and_b32_e32 v84, 0x7fffffff, v83
	v_cndmask_b32_e64 v85, v30, v84, s[84:85]
	v_mul_f32_e32 v85, 0xbfb8aa3b, v85
	v_exp_f32_e32 v86, v85
	v_min_f32_e32 v147, 0, v83
	v_add_f32_e32 v87, 1.0, v86
	v_mad_u32_u24 v148, v69, 24, v75
	v_rcp_f32_e32 v144, v87
	v_log_f32_e32 v145, v87
	v_add_f32_e32 v146, -1.0, v87
	v_sub_f32_e32 v146, v146, v86
	v_mul_f32_e32 v146, v146, v144
	v_fma_f32 v145, v145, v124, -v146
	v_sub_f32_e32 v147, v147, v145
	v_mul_f32_e32 v147, 0x3fb8aa3b, v147
	v_cndmask_b32_e64 v147, v144, v147, s[84:85]
	global_store_dword v148, v147, s[80:81]
	v_add_f32_e32 v149, v31, v72
	v_and_b32_e32 v150, 0x7fffffff, v149
	v_cndmask_b32_e64 v151, v31, v150, s[84:85]
	v_mul_f32_e32 v151, 0xbfb8aa3b, v151
	v_exp_f32_e32 v152, v151
	v_min_f32_e32 v181, 0, v149
	v_add_f32_e32 v153, 1.0, v152
	v_mad_u32_u24 v182, v69, 25, v75
	v_rcp_f32_e32 v154, v153
	v_log_f32_e32 v155, v153
	v_add_f32_e32 v180, -1.0, v153
	v_sub_f32_e32 v180, v180, v152
	v_mul_f32_e32 v180, v180, v154
	v_fma_f32 v155, v155, v124, -v180
	v_sub_f32_e32 v181, v181, v155
	v_mul_f32_e32 v181, 0x3fb8aa3b, v181
	v_cndmask_b32_e64 v181, v154, v181, s[84:85]
	global_store_dword v182, v181, s[80:81]
	v_add_f32_e32 v83, v32, v72
	v_and_b32_e32 v84, 0x7fffffff, v83
	v_cndmask_b32_e64 v85, v32, v84, s[84:85]
	v_mul_f32_e32 v85, 0xbfb8aa3b, v85
	v_exp_f32_e32 v86, v85
	v_min_f32_e32 v147, 0, v83
	v_add_f32_e32 v87, 1.0, v86
	v_mad_u32_u24 v148, v69, 26, v75
	v_rcp_f32_e32 v144, v87
	v_log_f32_e32 v145, v87
	v_add_f32_e32 v146, -1.0, v87
	v_sub_f32_e32 v146, v146, v86
	v_mul_f32_e32 v146, v146, v144
	v_fma_f32 v145, v145, v124, -v146
	v_sub_f32_e32 v147, v147, v145
	v_mul_f32_e32 v147, 0x3fb8aa3b, v147
	v_cndmask_b32_e64 v147, v144, v147, s[84:85]
	global_store_dword v148, v147, s[80:81]
	v_add_f32_e32 v149, v33, v72
	v_and_b32_e32 v150, 0x7fffffff, v149
	v_cndmask_b32_e64 v151, v33, v150, s[84:85]
	v_mul_f32_e32 v151, 0xbfb8aa3b, v151
	v_exp_f32_e32 v152, v151
	v_min_f32_e32 v181, 0, v149
	v_add_f32_e32 v153, 1.0, v152
	v_mad_u32_u24 v182, v69, 27, v75
	v_rcp_f32_e32 v154, v153
	v_log_f32_e32 v155, v153
	v_add_f32_e32 v180, -1.0, v153
	v_sub_f32_e32 v180, v180, v152
	v_mul_f32_e32 v180, v180, v154
	v_fma_f32 v155, v155, v124, -v180
	v_sub_f32_e32 v181, v181, v155
	v_mul_f32_e32 v181, 0x3fb8aa3b, v181
	v_cndmask_b32_e64 v181, v154, v181, s[84:85]
	global_store_dword v182, v181, s[80:81]
	v_add_f32_e32 v83, v2, v72
	v_and_b32_e32 v84, 0x7fffffff, v83
	v_cndmask_b32_e64 v85, v2, v84, s[84:85]
	v_mul_f32_e32 v85, 0xbfb8aa3b, v85
	v_exp_f32_e32 v86, v85
	v_min_f32_e32 v147, 0, v83
	v_add_f32_e32 v87, 1.0, v86
	v_mad_u32_u24 v148, v69, 32, v75
	v_rcp_f32_e32 v144, v87
	v_log_f32_e32 v145, v87
	v_add_f32_e32 v146, -1.0, v87
	v_sub_f32_e32 v146, v146, v86
	v_mul_f32_e32 v146, v146, v144
	v_fma_f32 v145, v145, v124, -v146
	v_sub_f32_e32 v147, v147, v145
	v_mul_f32_e32 v147, 0x3fb8aa3b, v147
	v_cndmask_b32_e64 v147, v144, v147, s[84:85]
	global_store_dword v148, v147, s[80:81]
	v_add_f32_e32 v149, v3, v72
	v_and_b32_e32 v150, 0x7fffffff, v149
	v_cndmask_b32_e64 v151, v3, v150, s[84:85]
	v_mul_f32_e32 v151, 0xbfb8aa3b, v151
	v_exp_f32_e32 v152, v151
	v_min_f32_e32 v181, 0, v149
	v_add_f32_e32 v153, 1.0, v152
	v_mad_u32_u24 v182, v69, 33, v75
	v_rcp_f32_e32 v154, v153
	v_log_f32_e32 v155, v153
	v_add_f32_e32 v180, -1.0, v153
	v_sub_f32_e32 v180, v180, v152
	v_mul_f32_e32 v180, v180, v154
	v_fma_f32 v155, v155, v124, -v180
	v_sub_f32_e32 v181, v181, v155
	v_mul_f32_e32 v181, 0x3fb8aa3b, v181
	v_cndmask_b32_e64 v181, v154, v181, s[84:85]
	global_store_dword v182, v181, s[80:81]
	v_add_f32_e32 v83, v4, v72
	v_and_b32_e32 v84, 0x7fffffff, v83
	v_cndmask_b32_e64 v85, v4, v84, s[84:85]
	v_mul_f32_e32 v85, 0xbfb8aa3b, v85
	v_exp_f32_e32 v86, v85
	v_min_f32_e32 v147, 0, v83
	v_add_f32_e32 v87, 1.0, v86
	v_mad_u32_u24 v148, v69, 34, v75
	v_rcp_f32_e32 v144, v87
	v_log_f32_e32 v145, v87
	v_add_f32_e32 v146, -1.0, v87
	v_sub_f32_e32 v146, v146, v86
	v_mul_f32_e32 v146, v146, v144
	v_fma_f32 v145, v145, v124, -v146
	v_sub_f32_e32 v147, v147, v145
	v_mul_f32_e32 v147, 0x3fb8aa3b, v147
	v_cndmask_b32_e64 v147, v144, v147, s[84:85]
	global_store_dword v148, v147, s[80:81]
	v_add_f32_e32 v149, v5, v72
	v_and_b32_e32 v150, 0x7fffffff, v149
	v_cndmask_b32_e64 v151, v5, v150, s[84:85]
	v_mul_f32_e32 v151, 0xbfb8aa3b, v151
	v_exp_f32_e32 v152, v151
	v_min_f32_e32 v181, 0, v149
	v_add_f32_e32 v153, 1.0, v152
	v_mad_u32_u24 v182, v69, 35, v75
	v_rcp_f32_e32 v154, v153
	v_log_f32_e32 v155, v153
	v_add_f32_e32 v180, -1.0, v153
	v_sub_f32_e32 v180, v180, v152
	v_mul_f32_e32 v180, v180, v154
	v_fma_f32 v155, v155, v124, -v180
	v_sub_f32_e32 v181, v181, v155
	v_mul_f32_e32 v181, 0x3fb8aa3b, v181
	v_cndmask_b32_e64 v181, v154, v181, s[84:85]
	global_store_dword v182, v181, s[80:81]
	v_add_f32_e32 v83, v6, v72
	v_and_b32_e32 v84, 0x7fffffff, v83
	v_cndmask_b32_e64 v85, v6, v84, s[84:85]
	v_mul_f32_e32 v85, 0xbfb8aa3b, v85
	v_exp_f32_e32 v86, v85
	v_min_f32_e32 v147, 0, v83
	v_add_f32_e32 v87, 1.0, v86
	v_mad_u32_u24 v148, v69, 40, v75
	v_rcp_f32_e32 v144, v87
	v_log_f32_e32 v145, v87
	v_add_f32_e32 v146, -1.0, v87
	v_sub_f32_e32 v146, v146, v86
	v_mul_f32_e32 v146, v146, v144
	v_fma_f32 v145, v145, v124, -v146
	v_sub_f32_e32 v147, v147, v145
	v_mul_f32_e32 v147, 0x3fb8aa3b, v147
	v_cndmask_b32_e64 v147, v144, v147, s[84:85]
	global_store_dword v148, v147, s[80:81]
	v_add_f32_e32 v149, v7, v72
	v_and_b32_e32 v150, 0x7fffffff, v149
	v_cndmask_b32_e64 v151, v7, v150, s[84:85]
	v_mul_f32_e32 v151, 0xbfb8aa3b, v151
	v_exp_f32_e32 v152, v151
	v_min_f32_e32 v181, 0, v149
	v_add_f32_e32 v153, 1.0, v152
	v_mad_u32_u24 v182, v69, 41, v75
	v_rcp_f32_e32 v154, v153
	v_log_f32_e32 v155, v153
	v_add_f32_e32 v180, -1.0, v153
	v_sub_f32_e32 v180, v180, v152
	v_mul_f32_e32 v180, v180, v154
	v_fma_f32 v155, v155, v124, -v180
	v_sub_f32_e32 v181, v181, v155
	v_mul_f32_e32 v181, 0x3fb8aa3b, v181
	v_cndmask_b32_e64 v181, v154, v181, s[84:85]
	global_store_dword v182, v181, s[80:81]
	v_add_f32_e32 v83, v8, v72
	v_and_b32_e32 v84, 0x7fffffff, v83
	v_cndmask_b32_e64 v85, v8, v84, s[84:85]
	v_mul_f32_e32 v85, 0xbfb8aa3b, v85
	v_exp_f32_e32 v86, v85
	v_min_f32_e32 v147, 0, v83
	v_add_f32_e32 v87, 1.0, v86
	v_mad_u32_u24 v148, v69, 42, v75
	v_rcp_f32_e32 v144, v87
	v_log_f32_e32 v145, v87
	v_add_f32_e32 v146, -1.0, v87
	v_sub_f32_e32 v146, v146, v86
	v_mul_f32_e32 v146, v146, v144
	v_fma_f32 v145, v145, v124, -v146
	v_sub_f32_e32 v147, v147, v145
	v_mul_f32_e32 v147, 0x3fb8aa3b, v147
	v_cndmask_b32_e64 v147, v144, v147, s[84:85]
	global_store_dword v148, v147, s[80:81]
	v_add_f32_e32 v149, v9, v72
	v_and_b32_e32 v150, 0x7fffffff, v149
	v_cndmask_b32_e64 v151, v9, v150, s[84:85]
	v_mul_f32_e32 v151, 0xbfb8aa3b, v151
	v_exp_f32_e32 v152, v151
	v_min_f32_e32 v181, 0, v149
	v_add_f32_e32 v153, 1.0, v152
	v_mad_u32_u24 v182, v69, 43, v75
	v_rcp_f32_e32 v154, v153
	v_log_f32_e32 v155, v153
	v_add_f32_e32 v180, -1.0, v153
	v_sub_f32_e32 v180, v180, v152
	v_mul_f32_e32 v180, v180, v154
	v_fma_f32 v155, v155, v124, -v180
	v_sub_f32_e32 v181, v181, v155
	v_mul_f32_e32 v181, 0x3fb8aa3b, v181
	v_cndmask_b32_e64 v181, v154, v181, s[84:85]
	global_store_dword v182, v181, s[80:81]
	v_add_f32_e32 v83, v10, v72
	v_and_b32_e32 v84, 0x7fffffff, v83
	v_cndmask_b32_e64 v85, v10, v84, s[84:85]
	v_mul_f32_e32 v85, 0xbfb8aa3b, v85
	v_exp_f32_e32 v86, v85
	v_min_f32_e32 v147, 0, v83
	v_add_f32_e32 v87, 1.0, v86
	v_mad_u32_u24 v148, v69, 48, v75
	v_rcp_f32_e32 v144, v87
	v_log_f32_e32 v145, v87
	v_add_f32_e32 v146, -1.0, v87
	v_sub_f32_e32 v146, v146, v86
	v_mul_f32_e32 v146, v146, v144
	v_fma_f32 v145, v145, v124, -v146
	v_sub_f32_e32 v147, v147, v145
	v_mul_f32_e32 v147, 0x3fb8aa3b, v147
	v_cndmask_b32_e64 v147, v144, v147, s[84:85]
	global_store_dword v148, v147, s[80:81]
	v_add_f32_e32 v149, v11, v72
	v_and_b32_e32 v150, 0x7fffffff, v149
	v_cndmask_b32_e64 v151, v11, v150, s[84:85]
	v_mul_f32_e32 v151, 0xbfb8aa3b, v151
	v_exp_f32_e32 v152, v151
	v_min_f32_e32 v181, 0, v149
	v_add_f32_e32 v153, 1.0, v152
	v_mad_u32_u24 v182, v69, 49, v75
	v_rcp_f32_e32 v154, v153
	v_log_f32_e32 v155, v153
	v_add_f32_e32 v180, -1.0, v153
	v_sub_f32_e32 v180, v180, v152
	v_mul_f32_e32 v180, v180, v154
	v_fma_f32 v155, v155, v124, -v180
	v_sub_f32_e32 v181, v181, v155
	v_mul_f32_e32 v181, 0x3fb8aa3b, v181
	v_cndmask_b32_e64 v181, v154, v181, s[84:85]
	global_store_dword v182, v181, s[80:81]
	v_add_f32_e32 v83, v12, v72
	v_and_b32_e32 v84, 0x7fffffff, v83
	v_cndmask_b32_e64 v85, v12, v84, s[84:85]
	v_mul_f32_e32 v85, 0xbfb8aa3b, v85
	v_exp_f32_e32 v86, v85
	v_min_f32_e32 v147, 0, v83
	v_add_f32_e32 v87, 1.0, v86
	v_mad_u32_u24 v148, v69, 50, v75
	v_rcp_f32_e32 v144, v87
	v_log_f32_e32 v145, v87
	v_add_f32_e32 v146, -1.0, v87
	v_sub_f32_e32 v146, v146, v86
	v_mul_f32_e32 v146, v146, v144
	v_fma_f32 v145, v145, v124, -v146
	v_sub_f32_e32 v147, v147, v145
	v_mul_f32_e32 v147, 0x3fb8aa3b, v147
	v_cndmask_b32_e64 v147, v144, v147, s[84:85]
	global_store_dword v148, v147, s[80:81]
	v_add_f32_e32 v149, v13, v72
	v_and_b32_e32 v150, 0x7fffffff, v149
	v_cndmask_b32_e64 v151, v13, v150, s[84:85]
	v_mul_f32_e32 v151, 0xbfb8aa3b, v151
	v_exp_f32_e32 v152, v151
	v_min_f32_e32 v181, 0, v149
	v_add_f32_e32 v153, 1.0, v152
	v_mad_u32_u24 v182, v69, 51, v75
	v_rcp_f32_e32 v154, v153
	v_log_f32_e32 v155, v153
	v_add_f32_e32 v180, -1.0, v153
	v_sub_f32_e32 v180, v180, v152
	v_mul_f32_e32 v180, v180, v154
	v_fma_f32 v155, v155, v124, -v180
	v_sub_f32_e32 v181, v181, v155
	v_mul_f32_e32 v181, 0x3fb8aa3b, v181
	v_cndmask_b32_e64 v181, v154, v181, s[84:85]
	global_store_dword v182, v181, s[80:81]
	v_add_f32_e32 v83, v14, v72
	v_and_b32_e32 v84, 0x7fffffff, v83
	v_cndmask_b32_e64 v85, v14, v84, s[84:85]
	v_mul_f32_e32 v85, 0xbfb8aa3b, v85
	v_exp_f32_e32 v86, v85
	v_min_f32_e32 v147, 0, v83
	v_add_f32_e32 v87, 1.0, v86
	v_mad_u32_u24 v148, v69, 56, v75
	v_rcp_f32_e32 v144, v87
	v_log_f32_e32 v145, v87
	v_add_f32_e32 v146, -1.0, v87
	v_sub_f32_e32 v146, v146, v86
	v_mul_f32_e32 v146, v146, v144
	v_fma_f32 v145, v145, v124, -v146
	v_sub_f32_e32 v147, v147, v145
	v_mul_f32_e32 v147, 0x3fb8aa3b, v147
	v_cndmask_b32_e64 v147, v144, v147, s[84:85]
	global_store_dword v148, v147, s[80:81]
	v_add_f32_e32 v149, v15, v72
	v_and_b32_e32 v150, 0x7fffffff, v149
	v_cndmask_b32_e64 v151, v15, v150, s[84:85]
	v_mul_f32_e32 v151, 0xbfb8aa3b, v151
	v_exp_f32_e32 v152, v151
	v_min_f32_e32 v181, 0, v149
	v_add_f32_e32 v153, 1.0, v152
	v_mad_u32_u24 v182, v69, 57, v75
	v_rcp_f32_e32 v154, v153
	v_log_f32_e32 v155, v153
	v_add_f32_e32 v180, -1.0, v153
	v_sub_f32_e32 v180, v180, v152
	v_mul_f32_e32 v180, v180, v154
	v_fma_f32 v155, v155, v124, -v180
	v_sub_f32_e32 v181, v181, v155
	v_mul_f32_e32 v181, 0x3fb8aa3b, v181
	v_cndmask_b32_e64 v181, v154, v181, s[84:85]
	global_store_dword v182, v181, s[80:81]
	v_add_f32_e32 v83, v16, v72
	v_and_b32_e32 v84, 0x7fffffff, v83
	v_cndmask_b32_e64 v85, v16, v84, s[84:85]
	v_mul_f32_e32 v85, 0xbfb8aa3b, v85
	v_exp_f32_e32 v86, v85
	v_min_f32_e32 v147, 0, v83
	v_add_f32_e32 v87, 1.0, v86
	v_mad_u32_u24 v148, v69, 58, v75
	v_rcp_f32_e32 v144, v87
	v_log_f32_e32 v145, v87
	v_add_f32_e32 v146, -1.0, v87
	v_sub_f32_e32 v146, v146, v86
	v_mul_f32_e32 v146, v146, v144
	v_fma_f32 v145, v145, v124, -v146
	v_sub_f32_e32 v147, v147, v145
	v_mul_f32_e32 v147, 0x3fb8aa3b, v147
	v_cndmask_b32_e64 v147, v144, v147, s[84:85]
	global_store_dword v148, v147, s[80:81]
	v_add_f32_e32 v149, v17, v72
	v_and_b32_e32 v150, 0x7fffffff, v149
	v_cndmask_b32_e64 v151, v17, v150, s[84:85]
	v_mul_f32_e32 v151, 0xbfb8aa3b, v151
	v_exp_f32_e32 v152, v151
	v_min_f32_e32 v181, 0, v149
	v_add_f32_e32 v153, 1.0, v152
	v_mad_u32_u24 v182, v69, 59, v75
	v_rcp_f32_e32 v154, v153
	v_log_f32_e32 v155, v153
	v_add_f32_e32 v180, -1.0, v153
	v_sub_f32_e32 v180, v180, v152
	v_mul_f32_e32 v180, v180, v154
	v_fma_f32 v155, v155, v124, -v180
	v_sub_f32_e32 v181, v181, v155
	v_mul_f32_e32 v181, 0x3fb8aa3b, v181
	v_cndmask_b32_e64 v181, v154, v181, s[84:85]
	global_store_dword v182, v181, s[80:81]
.Lep_cat4_done:
	s_or_b64 exec, exec, s[92:93]
	s_branch .LBB0_173
